# memory cross-attention K/V LDS staging: 8 first-touch loads batched before one wait (both layers)
# baseline (speedup 1.0000x reference)
.LBB0_638:
	global_load_dwordx4 v[100:103], v[0:1], off
	v_lshl_add_u64 v[0:1], v[0:1], 0, s[6:7]
	global_load_dwordx4 v[104:107], v[0:1], off
	v_lshl_add_u64 v[0:1], v[0:1], 0, s[6:7]
	global_load_dwordx4 v[108:111], v[0:1], off
	v_lshl_add_u64 v[0:1], v[0:1], 0, s[6:7]
	global_load_dwordx4 v[112:115], v[0:1], off
	v_lshl_add_u64 v[0:1], v[0:1], 0, s[6:7]
	v_mov_b32_e32 v116, v2
	v_add_u32_e32 v2, 0x9000, v2
	s_or_b64 exec, exec, s[4:5]
	v_lshrrev_b32_e32 v0, 5, v176
	s_movk_i32 s4, 0x210
	v_mul_lo_u32 v1, v0, s4
	v_and_b32_e32 v3, 0x1f0, v5
	s_mov_b32 s4, 0x9000
	v_add3_u32 v2, v1, v3, s4
	s_and_b32 s4, s90, 7
	v_lshlrev_b32_e32 v0, 8, v0
	v_lshl_add_u32 v0, s4, 14, v0
	v_mov_b32_e32 v1, 0
	v_lshlrev_b64 v[0:1], 1, v[0:1]
	v_or_b32_e32 v0, v0, v3
	v_lshl_add_u64 v[0:1], s[2:3], 0, v[0:1]
	s_mov_b64 s[4:5], 0x1f888000
	v_lshl_add_u64 v[0:1], v[0:1], 0, s[4:5]
	s_mov_b64 s[4:5], 0
	s_mov_b64 s[6:7], 0x2000
	s_movk_i32 s9, 0x5ff
.LBB0_640:
	global_load_dwordx4 v[120:123], v[0:1], off
	v_lshl_add_u64 v[0:1], v[0:1], 0, s[6:7]
	global_load_dwordx4 v[124:127], v[0:1], off
	v_lshl_add_u64 v[0:1], v[0:1], 0, s[6:7]
	global_load_dwordx4 v[128:131], v[0:1], off
	v_lshl_add_u64 v[0:1], v[0:1], 0, s[6:7]
	global_load_dwordx4 v[132:135], v[0:1], off
	v_lshl_add_u64 v[0:1], v[0:1], 0, s[6:7]
	v_mov_b32_e32 v136, v2
	v_add_u32_e32 v2, 0x8400, v2
	s_waitcnt vmcnt(0)
	ds_write_b128 v116, v[100:103]
	ds_write_b128 v116, v[104:107] offset:9216
	ds_write_b128 v116, v[108:111] offset:18432
	ds_write_b128 v116, v[112:115] offset:27648
	ds_write_b128 v136, v[120:123]
	ds_write_b128 v136, v[124:127] offset:8448
	ds_write_b128 v136, v[128:131] offset:16896
	ds_write_b128 v136, v[132:135] offset:25344
	s_or_b64 exec, exec, s[4:5]
	v_lshrrev_b32_e32 v0, 6, v176
	s_and_b32 s4, s90, -8
	v_add_u32_e32 v96, s4, v0
	s_movk_i32 s4, 0x400
	v_cmp_gt_i32_e32 vcc, s4, v96
	s_waitcnt lgkmcnt(0)
	s_barrier
	s_and_saveexec_b64 s[4:5], vcc
	s_cbranch_execz .LBB0_644
	v_bfe_u32 v2, v176, 4, 2
	v_and_b32_e32 v1, 15, v176
	s_movk_i32 s6, 0x2100
	v_mov_b32_e32 v3, 0x11400
	v_mad_u32_u24 v0, v0, s6, v3
	v_lshlrev_b32_e32 v3, 1, v1
	v_lshlrev_b32_e32 v6, 4, v2
	s_movk_i32 s6, 0x90
	v_or_b32_e32 v4, v0, v3
	v_mad_u32_u24 v105, v1, s6, v6
	s_movk_i32 s6, 0x840
	v_mad_u32_u24 v109, v2, s6, v4
	s_lshl_b32 s6, s90, 23
	s_and_b32 s6, s6, 0x2000000
	s_add_u32 s2, s2, s8
	v_mul_u32_u24_e32 v5, 0x210, v1
	v_mov_b32_e32 v99, 0
	s_addc_u32 s3, s3, 0
	v_add3_u32 v104, v0, v5, v6
	v_or_b32_e32 v0, 16, v1
	v_mov_b32_e32 v97, v99
	s_add_u32 s2, s2, s6
	v_mul_u32_u24_e32 v4, 0x210, v0
	v_lshl_or_b32 v98, v1, 11, v6
	s_mov_b32 s35, 0
	v_lshlrev_b64 v[0:1], 15, v[96:97]
	s_addc_u32 s3, s3, 0
	v_add_u32_e32 v106, 0x900, v105
	v_add_u32_e32 v107, 0x1200, v105
	v_add_u32_e32 v108, 0x1b00, v105
	v_lshl_add_u64 v[100:101], s[2:3], 0, v[0:1]
	s_lshl_b64 s[2:3], s[34:35], 15
	v_lshl_or_b32 v102, v2, 13, v3
	v_mov_b32_e32 v103, v99
	s_mov_b64 s[6:7], 0
	s_mov_b32 s8, 0x1b400000
	s_movk_i32 s9, 0x7fff
	v_add_u32_e32 v97, v6, v5
	v_add_u32_e32 v110, v6, v4
	s_mov_b32 s10, 0x1b401000
	s_movk_i32 s11, 0x3ff

.LBB0_2088:
	global_load_dwordx4 v[100:103], v[0:1], off
	v_lshl_add_u64 v[0:1], v[0:1], 0, s[8:9]
	global_load_dwordx4 v[104:107], v[0:1], off
	v_lshl_add_u64 v[0:1], v[0:1], 0, s[8:9]
	global_load_dwordx4 v[108:111], v[0:1], off
	v_lshl_add_u64 v[0:1], v[0:1], 0, s[8:9]
	global_load_dwordx4 v[112:115], v[0:1], off
	v_lshl_add_u64 v[0:1], v[0:1], 0, s[8:9]
	v_mov_b32_e32 v116, v2
	v_add_u32_e32 v2, 0x9000, v2
	s_or_b64 exec, exec, s[6:7]
	v_lshrrev_b32_e32 v0, 5, v176
	s_movk_i32 s5, 0x210
	v_mul_lo_u32 v1, v0, s5
	v_and_b32_e32 v3, 0x1f0, v5
	s_mov_b32 s5, 0x9000
	v_add3_u32 v2, v1, v3, s5
	s_and_b32 s5, s90, 7
	v_lshlrev_b32_e32 v0, 8, v0
	v_lshl_add_u32 v0, s5, 14, v0
	v_mov_b32_e32 v1, 0
	v_lshlrev_b64 v[0:1], 1, v[0:1]
	v_or_b32_e32 v0, v0, v3
	v_lshl_add_u64 v[0:1], s[2:3], 0, v[0:1]
	s_mov_b64 s[6:7], 0x1f8c8000
	v_lshl_add_u64 v[0:1], v[0:1], 0, s[6:7]
	s_mov_b64 s[6:7], 0
	s_mov_b64 s[8:9], 0x2000
	s_movk_i32 s5, 0x5ff
.LBB0_2090:
	global_load_dwordx4 v[120:123], v[0:1], off
	v_lshl_add_u64 v[0:1], v[0:1], 0, s[8:9]
	global_load_dwordx4 v[124:127], v[0:1], off
	v_lshl_add_u64 v[0:1], v[0:1], 0, s[8:9]
	global_load_dwordx4 v[128:131], v[0:1], off
	v_lshl_add_u64 v[0:1], v[0:1], 0, s[8:9]
	global_load_dwordx4 v[132:135], v[0:1], off
	v_lshl_add_u64 v[0:1], v[0:1], 0, s[8:9]
	v_mov_b32_e32 v136, v2
	v_add_u32_e32 v2, 0x8400, v2
	s_waitcnt vmcnt(0)
	ds_write_b128 v116, v[100:103]
	ds_write_b128 v116, v[104:107] offset:9216
	ds_write_b128 v116, v[108:111] offset:18432
	ds_write_b128 v116, v[112:115] offset:27648
	ds_write_b128 v136, v[120:123]
	ds_write_b128 v136, v[124:127] offset:8448
	ds_write_b128 v136, v[128:131] offset:16896
	ds_write_b128 v136, v[132:135] offset:25344
	s_or_b64 exec, exec, s[6:7]
	s_and_b32 s5, s90, -8
	v_add_u32_e32 v96, s5, v179
	s_movk_i32 s5, 0x400
	v_cmp_gt_i32_e32 vcc, s5, v96
	s_waitcnt lgkmcnt(0)
	s_barrier
	s_and_saveexec_b64 s[6:7], vcc
	s_cbranch_execz .LBB0_2094
	s_lshl_b32 s8, s90, 23
	s_and_b32 s8, s8, 0x2000000
	v_bfe_u32 v2, v176, 4, 2
	v_and_b32_e32 v0, 15, v176
	s_movk_i32 s5, 0x2100
	v_mov_b32_e32 v1, 0x11400
	s_add_u32 s2, s2, s10
	v_mad_u32_u24 v1, v179, s5, v1
	v_lshlrev_b32_e32 v3, 1, v0
	v_mul_u32_u24_e32 v5, 0x210, v0
	v_lshlrev_b32_e32 v6, 4, v2
	s_movk_i32 s5, 0x90
	v_mov_b32_e32 v99, 0
	s_addc_u32 s3, s3, 0
	v_or_b32_e32 v4, v1, v3
	v_add3_u32 v104, v1, v5, v6
	v_mad_u32_u24 v105, v0, s5, v6
	v_or_b32_e32 v1, 16, v0
	s_movk_i32 s5, 0x840
	v_mov_b32_e32 v97, v99
	s_add_u32 s2, s2, s8
	v_mad_u32_u24 v109, v2, s5, v4
	v_mul_u32_u24_e32 v4, 0x210, v1
	v_lshl_or_b32 v98, v0, 11, v6
	s_mov_b32 s5, 0
	v_lshlrev_b64 v[0:1], 15, v[96:97]
	s_addc_u32 s3, s3, 0
	v_add_u32_e32 v106, 0x900, v105
	v_add_u32_e32 v107, 0x1200, v105
	v_add_u32_e32 v108, 0x1b00, v105
	v_lshl_add_u64 v[100:101], s[2:3], 0, v[0:1]
	s_lshl_b64 s[2:3], s[4:5], 15
	v_lshl_or_b32 v102, v2, 13, v3
	v_mov_b32_e32 v103, v99
	s_mov_b64 s[8:9], 0
	s_mov_b32 s5, 0x1b400000
	s_movk_i32 s10, 0x7fff
	v_add_u32_e32 v97, v6, v5
	v_add_u32_e32 v110, v6, v4
	s_mov_b32 s11, 0x1b401000
	s_movk_i32 s12, 0x3ff
